# LayerNorm phase: rows fetched two iterations ahead through two register buffers, loop unrolled by two (arithmetic unchanged)
# speedup vs baseline: 1.0299x; 1.0101x over previous
; __device__ __forceinline__ unsigned pk2(float lo, float hi) { return f2bf(lo) | (f2bf(hi) << 16); }
; __device__ __forceinline__ void ln_phase(const float* Z, const float* g, const float* b, float* Xf, bf16_t* Xb, int gw, int NGW, int lane) {
;     ...
;     for (int m = gw; m < MTOK; m += NGW) {
;         f32x4 v[4]; float s = 0.f;
; #pragma unroll
;         for (int j = 0; j < 4; ++j) v[j] = nx[j];
;         if (m + NGW < MTOK) {
; #pragma unroll
;             for (int j = 0; j < 4; ++j) nx[j] = ((const f32x4*)(Z + (size_t)(m + NGW) * DM))[64 * j + lane];
;         }
; #pragma unroll
;         for (int j = 0; j < 4; ++j) s += (v[j][0] + v[j][1]) + (v[j][2] + v[j][3]);
;         const float mean = wave_sum(s) * (1.f / DM); float s2 = 0.f;
; #pragma unroll
;         for (int j = 0; j < 4; ++j) { v[j] = v[j] - mean; s2 += (v[j][0] * v[j][0] + v[j][1] * v[j][1]) + (v[j][2] * v[j][2] + v[j][3] * v[j][3]); }
;         const float rstd = 1.f / sqrtf(wave_sum(s2) * (1.f / DM) + 1e-5f);
;         f32x4* xo = (f32x4*)(Xf + (size_t)m * DM) + lane; u32x2* xb = (u32x2*)(Xb + (size_t)m * DM) + lane;
; #pragma unroll
;         for (int j = 0; j < 4; ++j) { const f32x4 o = v[j] * rstd * gv[j] + bv[j]; xo[64 * j] = o;
;             u32x2 w; w.x = pk2(o[0], o[1]); w.y = pk2(o[2], o[3]); xb[64 * j] = w; }
.Lln_entry:
	v_lshl_add_u64 v[112:113], s[88:89], 0, v[66:67]
	v_add_co_u32_e32 v112, vcc, 0x14800000, v112
	s_nop 1
	v_addc_co_u32_e32 v113, vcc, 0, v113, vcc
	global_load_dwordx4 v[46:49], v[112:113], off
	global_load_dwordx4 v[50:53], v[112:113], off offset:1024
	global_load_dwordx4 v[54:57], v[112:113], off offset:2048
	global_load_dwordx4 v[58:61], v[112:113], off offset:3072
	v_readlane_b32 s24, v255, 11
	v_readlane_b32 s25, v255, 12
	s_nop 1
	v_lshl_add_u64 v[112:113], v[66:67], 0, s[24:25]
	v_lshl_add_u64 v[112:113], s[88:89], 0, v[112:113]
	v_add_co_u32_e32 v112, vcc, 0x14800000, v112
	s_nop 1
	v_addc_co_u32_e32 v113, vcc, 0, v113, vcc
	global_load_dwordx4 v[96:99], v[112:113], off
	global_load_dwordx4 v[100:103], v[112:113], off offset:1024
	global_load_dwordx4 v[104:107], v[112:113], off offset:2048
	global_load_dwordx4 v[108:111], v[112:113], off offset:3072
.Lln_A:
	v_pk_add_f32 v[74:75], v[72:73], v[44:45]
	v_add_f32_e32 v43, v38, v39
	v_add_f32_e32 v33, v74, v75
	v_pk_add_f32 v[74:75], v[70:71], v[40:41]
	v_add_f32_e32 v69, 0, v33
	v_pk_add_f32 v[74:75], v[74:75], v[74:75] op_sel_hi:[0,1]
	v_add_f32_e32 v33, v36, v37
	v_mov_b32_e32 v35, v75
	v_pk_add_f32 v[76:77], v[32:33], v[42:43]
	v_pk_add_f32 v[74:75], v[34:35], v[68:69]
	v_mov_b32_e32 v35, v185
	v_pk_add_f32 v[74:75], v[76:77], v[74:75]
	v_lshl_add_u64 v[78:79], s[88:89], 0, v[64:65]
	v_add_f32_e32 v33, v74, v75
	v_readlane_b32 s26, v255, 15
	v_readlane_b32 s27, v255, 16
	v_add_f32_dpp v33, v33, v33 row_shr:1 row_mask:0xf bank_mask:0xf bound_ctrl:1
	s_nop 0
	v_lshl_add_u64 v[64:65], v[64:65], 0, s[26:27]
	v_add_f32_dpp v33, v33, v33 row_shr:2 row_mask:0xf bank_mask:0xf bound_ctrl:1
	s_nop 1
	v_add_f32_dpp v33, v33, v33 row_shr:4 row_mask:0xf bank_mask:0xf bound_ctrl:1
	s_nop 1
	v_add_f32_dpp v33, v33, v33 row_shr:8 row_mask:0xf bank_mask:0xf bound_ctrl:1
	s_nop 1
	v_mov_b32_dpp v35, v33 row_bcast:15 row_mask:0xa bank_mask:0xf
	v_add_f32_e32 v33, v33, v35
	v_mov_b32_e32 v35, v185
	s_nop 1
	v_mov_b32_dpp v35, v33 row_bcast:31 row_mask:0xc bank_mask:0xf
	v_add_f32_e32 v33, v33, v35
	s_nop 0
	v_readlane_b32 s0, v33, 63
	s_nop 1
	v_fmac_f32_e32 v45, s0, v227
	v_fmac_f32_e32 v72, s0, v227
	v_fmac_f32_e32 v73, s0, v227
	v_fmac_f32_e32 v44, s0, v227
	v_mul_f32_e32 v33, v72, v72
	v_mul_f32_e32 v35, v45, v45
	v_fmac_f32_e32 v33, v44, v44
	v_fmac_f32_e32 v35, v73, v73
	v_fmac_f32_e32 v41, s0, v227
	v_fmac_f32_e32 v70, s0, v227
	v_add_f32_e32 v33, v33, v35
	v_fmac_f32_e32 v71, s0, v227
	v_fmac_f32_e32 v40, s0, v227
	v_mul_f32_e32 v35, v70, v70
	v_mul_f32_e32 v43, v41, v41
	v_fmac_f32_e32 v35, v40, v40
	v_fmac_f32_e32 v43, v71, v71
	v_add_f32_e32 v35, v35, v43
	v_fmac_f32_e32 v39, s0, v227
	v_fmac_f32_e32 v37, s0, v227
	v_add_f32_e32 v33, v33, v35
	v_fmac_f32_e32 v38, s0, v227
	v_fmac_f32_e32 v36, s0, v227
	v_mul_f32_e32 v35, v37, v37
	v_mul_f32_e32 v43, v39, v39
	v_fmac_f32_e32 v35, v36, v36
	v_fmac_f32_e32 v43, v38, v38
	v_add_f32_e32 v35, v35, v43
	v_fmac_f32_e32 v68, s0, v227
	v_fmac_f32_e32 v42, s0, v227
	v_add_f32_e32 v33, v35, v33
	v_fmac_f32_e32 v34, s0, v227
	v_fmac_f32_e32 v32, s0, v227
	v_mul_f32_e32 v35, v42, v42
	v_mul_f32_e32 v43, v68, v68
	v_fmac_f32_e32 v35, v32, v32
	v_fmac_f32_e32 v43, v34, v34
	v_add_f32_e32 v35, v35, v43
	v_add_f32_e32 v33, v35, v33
	v_mov_b32_e32 v35, v185
	s_nop 0
	v_add_f32_dpp v33, v33, v33 row_shr:1 row_mask:0xf bank_mask:0xf bound_ctrl:1
	s_nop 1
	v_add_f32_dpp v33, v33, v33 row_shr:2 row_mask:0xf bank_mask:0xf bound_ctrl:1
	s_nop 1
	v_add_f32_dpp v33, v33, v33 row_shr:4 row_mask:0xf bank_mask:0xf bound_ctrl:1
	s_nop 1
	v_add_f32_dpp v33, v33, v33 row_shr:8 row_mask:0xf bank_mask:0xf bound_ctrl:1
	s_nop 1
	v_mov_b32_dpp v35, v33 row_bcast:15 row_mask:0xa bank_mask:0xf
	v_add_f32_e32 v33, v33, v35
	v_mov_b32_e32 v35, v185
	s_nop 1
	v_mov_b32_dpp v35, v33 row_bcast:31 row_mask:0xc bank_mask:0xf
	v_add_f32_e32 v33, v33, v35
	s_nop 0
	v_readlane_b32 s0, v33, 63
	v_mov_b32_e32 v33, 0x3727c5ac
	s_nop 0
	v_fma_f32 v33, s0, v228, v33
	s_mov_b32 s0, 0xf800000
	v_mul_f32_e32 v35, 0x4f800000, v33
	v_cmp_gt_f32_e32 vcc, s0, v33
	s_mov_b32 s0, 0x8200000
	s_nop 0
	v_cndmask_b32_e32 v33, v33, v35, vcc
	v_sqrt_f32_e32 v35, v33
	s_nop 0
	v_add_u32_e32 v43, -1, v35
	v_fma_f32 v69, -v43, v35, v33
	v_cmp_ge_f32_e64 s[36:37], 0, v69
	v_add_u32_e32 v69, 1, v35
	s_nop 0
	v_cndmask_b32_e64 v43, v35, v43, s[36:37]
	v_fma_f32 v35, -v69, v35, v33
	v_cmp_lt_f32_e64 s[36:37], 0, v35
	s_nop 1
	v_cndmask_b32_e64 v35, v43, v69, s[36:37]
	v_mul_f32_e32 v43, 0x37800000, v35
	v_cndmask_b32_e32 v35, v35, v43, vcc
	v_mov_b32_e32 v43, 0x260
	v_cmp_class_f32_e32 vcc, v33, v43
	s_nop 1
	v_cndmask_b32_e32 v33, v35, v33, vcc
	v_div_scale_f32 v35, s[24:25], v33, v33, 1.0
	v_rcp_f32_e32 v43, v35
	v_readlane_b32 s24, v255, 11
	v_readlane_b32 s25, v255, 12
	v_fma_f32 v69, -v35, v43, 1.0
	v_fmac_f32_e32 v43, v69, v43
	v_div_scale_f32 v69, vcc, 1.0, v33, 1.0
	v_mul_f32_e32 v74, v69, v43
	v_fma_f32 v75, -v35, v74, v69
	v_fmac_f32_e32 v74, v75, v43
	v_fma_f32 v35, -v35, v74, v69
	v_div_fmas_f32 v35, v35, v43, v74
	v_div_fixup_f32 v76, v35, v33, 1.0
	v_mov_b32_e32 v74, v44
	v_mov_b32_e32 v75, v72
	v_pk_mul_f32 v[80:81], v[74:75], v[76:77] op_sel_hi:[1,0]
	v_mov_b32_e32 v44, v73
	v_pk_fma_f32 v[72:73], v[0:1], v[80:81], v[4:5]
	v_pk_mul_f32 v[44:45], v[44:45], v[76:77] op_sel_hi:[1,0]
	v_bfe_u32 v33, v72, 16, 1
	v_add3_u32 v33, v72, v33, s6
	v_bfe_u32 v35, v73, 16, 1
	v_pk_fma_f32 v[74:75], v[2:3], v[44:45], v[6:7]
	v_lshrrev_b32_e32 v33, 16, v33
	v_add3_u32 v35, v73, v35, s6
	v_and_or_b32 v44, v35, s3, v33
	v_bfe_u32 v33, v74, 16, 1
	v_add3_u32 v33, v74, v33, s6
	v_bfe_u32 v35, v75, 16, 1
; __device__ __forceinline__ unsigned pk2(float lo, float hi) { return f2bf(lo) | (f2bf(hi) << 16); }
; __device__ __forceinline__ void ln_phase(const float* Z, const float* g, const float* b, float* Xf, bf16_t* Xb, int gw, int NGW, int lane) {
;     ...
;     for (int m = gw; m < MTOK; m += NGW) {
;         f32x4 v[4]; float s = 0.f;
; #pragma unroll
;         for (int j = 0; j < 4; ++j) v[j] = nx[j];
;         if (m + NGW < MTOK) {
; #pragma unroll
;             for (int j = 0; j < 4; ++j) nx[j] = ((const f32x4*)(Z + (size_t)(m + NGW) * DM))[64 * j + lane];
;         }
; #pragma unroll
;         for (int j = 0; j < 4; ++j) s += (v[j][0] + v[j][1]) + (v[j][2] + v[j][3]);
;         const float mean = wave_sum(s) * (1.f / DM); float s2 = 0.f;
; #pragma unroll
;         for (int j = 0; j < 4; ++j) { v[j] = v[j] - mean; s2 += (v[j][0] * v[j][0] + v[j][1] * v[j][1]) + (v[j][2] * v[j][2] + v[j][3] * v[j][3]); }
;         const float rstd = 1.f / sqrtf(wave_sum(s2) * (1.f / DM) + 1e-5f);
;         f32x4* xo = (f32x4*)(Xf + (size_t)m * DM) + lane; u32x2* xb = (u32x2*)(Xb + (size_t)m * DM) + lane;
; #pragma unroll
;         for (int j = 0; j < 4; ++j) { const f32x4 o = v[j] * rstd * gv[j] + bv[j]; xo[64 * j] = o;
;             u32x2 w; w.x = pk2(o[0], o[1]); w.y = pk2(o[2], o[3]); xb[64 * j] = w; }
	global_store_dwordx4 v[62:63], v[72:75], off
	v_lshrrev_b32_e32 v33, 16, v33
	v_add3_u32 v35, v75, v35, s6
	v_add_co_u32_e32 v74, vcc, s0, v78
	v_and_or_b32 v45, v35, s3, v33
	s_nop 0
	v_addc_co_u32_e32 v75, vcc, 0, v79, vcc
	global_store_dwordx2 v[74:75], v[44:45], off
	v_mov_b32_e32 v44, v40
	v_mov_b32_e32 v45, v70
	v_pk_mul_f32 v[44:45], v[44:45], v[76:77] op_sel_hi:[1,0]
	v_mov_b32_e32 v40, v71
	v_pk_fma_f32 v[70:71], v[8:9], v[44:45], v[12:13]
	v_pk_mul_f32 v[40:41], v[40:41], v[76:77] op_sel_hi:[1,0]
	v_bfe_u32 v33, v70, 16, 1
	v_add3_u32 v33, v70, v33, s6
	v_bfe_u32 v35, v71, 16, 1
	v_pk_fma_f32 v[72:73], v[10:11], v[40:41], v[14:15]
	v_lshrrev_b32_e32 v33, 16, v33
	v_add3_u32 v35, v71, v35, s6
	v_and_or_b32 v40, v35, s3, v33
	v_bfe_u32 v33, v72, 16, 1
	v_add3_u32 v33, v72, v33, s6
	v_bfe_u32 v35, v73, 16, 1
	v_pk_mul_f32 v[36:37], v[36:37], v[76:77] op_sel_hi:[1,0]
	v_lshrrev_b32_e32 v33, 16, v33
	v_add3_u32 v35, v73, v35, s6
	v_pk_fma_f32 v[36:37], v[16:17], v[36:37], v[20:21]
	v_and_or_b32 v41, v35, s3, v33
	v_bfe_u32 v33, v36, 16, 1
	v_pk_mul_f32 v[38:39], v[38:39], v[76:77] op_sel_hi:[1,0]
	v_add3_u32 v33, v36, v33, s6
	v_bfe_u32 v35, v37, 16, 1
	v_pk_fma_f32 v[38:39], v[18:19], v[38:39], v[22:23]
	v_lshrrev_b32_e32 v33, 16, v33
	v_add3_u32 v35, v37, v35, s6
	global_store_dwordx4 v[62:63], v[70:73], off offset:1024
	global_store_dwordx2 v[74:75], v[40:41], off offset:512
	global_store_dwordx4 v[62:63], v[36:39], off offset:2048
	v_lshl_add_u64 v[66:67], v[66:67], 0, s[24:25]
	s_andn2_b64 vcc, exec, s[12:13]
	v_and_or_b32 v36, v35, s3, v33
	v_bfe_u32 v33, v38, 16, 1
	v_add3_u32 v33, v38, v33, s6
	v_bfe_u32 v35, v39, 16, 1
	v_lshrrev_b32_e32 v33, 16, v33
	v_add3_u32 v35, v39, v35, s6
	v_and_or_b32 v37, v35, s3, v33
	v_mov_b32_e32 v33, v42
	v_pk_mul_f32 v[32:33], v[32:33], v[76:77] op_sel_hi:[1,0]
	v_mov_b32_e32 v35, v68
	v_pk_mul_f32 v[34:35], v[34:35], v[76:77] op_sel_hi:[1,0]
	v_pk_fma_f32 v[32:33], v[24:25], v[32:33], v[28:29]
	global_store_dwordx2 v[74:75], v[36:37], off offset:1024
	v_pk_fma_f32 v[34:35], v[26:27], v[34:35], v[30:31]
	v_bfe_u32 v36, v32, 16, 1
	global_store_dwordx4 v[62:63], v[32:35], off offset:3072
	v_lshl_add_u64 v[62:63], v[62:63], 0, s[24:25]
	s_nop 1
	v_add3_u32 v32, v32, v36, s6
	v_bfe_u32 v36, v33, 16, 1
	v_lshrrev_b32_e32 v32, 16, v32
	v_add3_u32 v33, v33, v36, s6
	v_and_or_b32 v32, v33, s3, v32
	v_bfe_u32 v33, v34, 16, 1
	v_add3_u32 v33, v34, v33, s6
	v_bfe_u32 v34, v35, 16, 1
	v_lshrrev_b32_e32 v33, 16, v33
	v_add3_u32 v34, v35, v34, s6
	v_and_or_b32 v33, v34, s3, v33
	global_store_dwordx2 v[74:75], v[32:33], off offset:1536
	v_readlane_b32 s12, v255, 13
	s_add_i32 s2, s2, s12
	s_cmpk_gt_i32 s2, 0x40ff
	s_cbranch_scc1 .LBB0_1645
	s_waitcnt vmcnt(12)
	v_mov_b32_e32 v44, v46
	v_mov_b32_e32 v72, v47
	v_mov_b32_e32 v73, v48
	v_mov_b32_e32 v45, v49
	v_mov_b32_e32 v40, v50
	v_mov_b32_e32 v70, v51
	v_mov_b32_e32 v71, v52
	v_mov_b32_e32 v41, v53
	v_mov_b32_e32 v36, v54
	v_mov_b32_e32 v37, v55
	v_mov_b32_e32 v38, v56
	v_mov_b32_e32 v39, v57
	v_mov_b32_e32 v32, v58
	v_mov_b32_e32 v42, v59
	v_mov_b32_e32 v34, v60
	v_mov_b32_e32 v68, v61
	s_lshl_b32 s13, s12, 1
	s_add_i32 s13, s13, s2
	s_cmpk_gt_i32 s13, 0x40ff
	s_cbranch_scc1 .Lln_A_noload
	v_lshl_add_u64 v[112:113], v[66:67], 0, s[24:25]
	v_lshl_add_u64 v[112:113], s[88:89], 0, v[112:113]
	v_add_co_u32_e32 v112, vcc, 0x14800000, v112
	s_nop 1
	v_addc_co_u32_e32 v113, vcc, 0, v113, vcc
	global_load_dwordx4 v[46:49], v[112:113], off
	global_load_dwordx4 v[50:53], v[112:113], off offset:1024
	global_load_dwordx4 v[54:57], v[112:113], off offset:2048
	global_load_dwordx4 v[58:61], v[112:113], off offset:3072
.Lln_A_noload:
.Lln_B:
	v_pk_add_f32 v[74:75], v[72:73], v[44:45]
	v_add_f32_e32 v43, v38, v39
	v_add_f32_e32 v33, v74, v75
	v_pk_add_f32 v[74:75], v[70:71], v[40:41]
	v_add_f32_e32 v69, 0, v33
	v_pk_add_f32 v[74:75], v[74:75], v[74:75] op_sel_hi:[0,1]
	v_add_f32_e32 v33, v36, v37
	v_mov_b32_e32 v35, v75
	v_pk_add_f32 v[76:77], v[32:33], v[42:43]
	v_pk_add_f32 v[74:75], v[34:35], v[68:69]
	v_mov_b32_e32 v35, v185
	v_pk_add_f32 v[74:75], v[76:77], v[74:75]
	v_lshl_add_u64 v[78:79], s[88:89], 0, v[64:65]
	v_add_f32_e32 v33, v74, v75
	v_readlane_b32 s26, v255, 15
	v_readlane_b32 s27, v255, 16
	v_add_f32_dpp v33, v33, v33 row_shr:1 row_mask:0xf bank_mask:0xf bound_ctrl:1
	s_nop 0
	v_lshl_add_u64 v[64:65], v[64:65], 0, s[26:27]
	v_add_f32_dpp v33, v33, v33 row_shr:2 row_mask:0xf bank_mask:0xf bound_ctrl:1
	s_nop 1
	v_add_f32_dpp v33, v33, v33 row_shr:4 row_mask:0xf bank_mask:0xf bound_ctrl:1
	s_nop 1
	v_add_f32_dpp v33, v33, v33 row_shr:8 row_mask:0xf bank_mask:0xf bound_ctrl:1
	s_nop 1
	v_mov_b32_dpp v35, v33 row_bcast:15 row_mask:0xa bank_mask:0xf
	v_add_f32_e32 v33, v33, v35
	v_mov_b32_e32 v35, v185
	s_nop 1
	v_mov_b32_dpp v35, v33 row_bcast:31 row_mask:0xc bank_mask:0xf
	v_add_f32_e32 v33, v33, v35
	s_nop 0
	v_readlane_b32 s0, v33, 63
	s_nop 1
	v_fmac_f32_e32 v45, s0, v227
	v_fmac_f32_e32 v72, s0, v227
	v_fmac_f32_e32 v73, s0, v227
	v_fmac_f32_e32 v44, s0, v227
	v_mul_f32_e32 v33, v72, v72
	v_mul_f32_e32 v35, v45, v45
	v_fmac_f32_e32 v33, v44, v44
	v_fmac_f32_e32 v35, v73, v73
	v_fmac_f32_e32 v41, s0, v227
	v_fmac_f32_e32 v70, s0, v227
	v_add_f32_e32 v33, v33, v35
	v_fmac_f32_e32 v71, s0, v227
	v_fmac_f32_e32 v40, s0, v227
	v_mul_f32_e32 v35, v70, v70
	v_mul_f32_e32 v43, v41, v41
	v_fmac_f32_e32 v35, v40, v40
	v_fmac_f32_e32 v43, v71, v71
	v_add_f32_e32 v35, v35, v43
	v_fmac_f32_e32 v39, s0, v227
	v_fmac_f32_e32 v37, s0, v227
	v_add_f32_e32 v33, v33, v35
	v_fmac_f32_e32 v38, s0, v227
	v_fmac_f32_e32 v36, s0, v227
	v_mul_f32_e32 v35, v37, v37
; __device__ __forceinline__ unsigned pk2(float lo, float hi) { return f2bf(lo) | (f2bf(hi) << 16); }
; __device__ __forceinline__ void ln_phase(const float* Z, const float* g, const float* b, float* Xf, bf16_t* Xb, int gw, int NGW, int lane) {
;     ...
;     for (int m = gw; m < MTOK; m += NGW) {
;         f32x4 v[4]; float s = 0.f;
; #pragma unroll
;         for (int j = 0; j < 4; ++j) v[j] = nx[j];
;         if (m + NGW < MTOK) {
; #pragma unroll
;             for (int j = 0; j < 4; ++j) nx[j] = ((const f32x4*)(Z + (size_t)(m + NGW) * DM))[64 * j + lane];
;         }
; #pragma unroll
;         for (int j = 0; j < 4; ++j) s += (v[j][0] + v[j][1]) + (v[j][2] + v[j][3]);
;         const float mean = wave_sum(s) * (1.f / DM); float s2 = 0.f;
; #pragma unroll
;         for (int j = 0; j < 4; ++j) { v[j] = v[j] - mean; s2 += (v[j][0] * v[j][0] + v[j][1] * v[j][1]) + (v[j][2] * v[j][2] + v[j][3] * v[j][3]); }
;         const float rstd = 1.f / sqrtf(wave_sum(s2) * (1.f / DM) + 1e-5f);
;         f32x4* xo = (f32x4*)(Xf + (size_t)m * DM) + lane; u32x2* xb = (u32x2*)(Xb + (size_t)m * DM) + lane;
; #pragma unroll
;         for (int j = 0; j < 4; ++j) { const f32x4 o = v[j] * rstd * gv[j] + bv[j]; xo[64 * j] = o;
;             u32x2 w; w.x = pk2(o[0], o[1]); w.y = pk2(o[2], o[3]); xb[64 * j] = w; }
	v_mul_f32_e32 v43, v39, v39
	v_fmac_f32_e32 v35, v36, v36
	v_fmac_f32_e32 v43, v38, v38
	v_add_f32_e32 v35, v35, v43
	v_fmac_f32_e32 v68, s0, v227
	v_fmac_f32_e32 v42, s0, v227
	v_add_f32_e32 v33, v35, v33
	v_fmac_f32_e32 v34, s0, v227
	v_fmac_f32_e32 v32, s0, v227
	v_mul_f32_e32 v35, v42, v42
	v_mul_f32_e32 v43, v68, v68
	v_fmac_f32_e32 v35, v32, v32
	v_fmac_f32_e32 v43, v34, v34
	v_add_f32_e32 v35, v35, v43
	v_add_f32_e32 v33, v35, v33
	v_mov_b32_e32 v35, v185
	s_nop 0
	v_add_f32_dpp v33, v33, v33 row_shr:1 row_mask:0xf bank_mask:0xf bound_ctrl:1
	s_nop 1
	v_add_f32_dpp v33, v33, v33 row_shr:2 row_mask:0xf bank_mask:0xf bound_ctrl:1
	s_nop 1
	v_add_f32_dpp v33, v33, v33 row_shr:4 row_mask:0xf bank_mask:0xf bound_ctrl:1
	s_nop 1
	v_add_f32_dpp v33, v33, v33 row_shr:8 row_mask:0xf bank_mask:0xf bound_ctrl:1
	s_nop 1
	v_mov_b32_dpp v35, v33 row_bcast:15 row_mask:0xa bank_mask:0xf
	v_add_f32_e32 v33, v33, v35
	v_mov_b32_e32 v35, v185
	s_nop 1
	v_mov_b32_dpp v35, v33 row_bcast:31 row_mask:0xc bank_mask:0xf
	v_add_f32_e32 v33, v33, v35
	s_nop 0
	v_readlane_b32 s0, v33, 63
	v_mov_b32_e32 v33, 0x3727c5ac
	s_nop 0
	v_fma_f32 v33, s0, v228, v33
	s_mov_b32 s0, 0xf800000
	v_mul_f32_e32 v35, 0x4f800000, v33
	v_cmp_gt_f32_e32 vcc, s0, v33
	s_mov_b32 s0, 0x8200000
	s_nop 0
	v_cndmask_b32_e32 v33, v33, v35, vcc
	v_sqrt_f32_e32 v35, v33
	s_nop 0
	v_add_u32_e32 v43, -1, v35
	v_fma_f32 v69, -v43, v35, v33
	v_cmp_ge_f32_e64 s[36:37], 0, v69
	v_add_u32_e32 v69, 1, v35
	s_nop 0
	v_cndmask_b32_e64 v43, v35, v43, s[36:37]
	v_fma_f32 v35, -v69, v35, v33
	v_cmp_lt_f32_e64 s[36:37], 0, v35
	s_nop 1
	v_cndmask_b32_e64 v35, v43, v69, s[36:37]
	v_mul_f32_e32 v43, 0x37800000, v35
	v_cndmask_b32_e32 v35, v35, v43, vcc
	v_mov_b32_e32 v43, 0x260
	v_cmp_class_f32_e32 vcc, v33, v43
	s_nop 1
	v_cndmask_b32_e32 v33, v35, v33, vcc
	v_div_scale_f32 v35, s[24:25], v33, v33, 1.0
	v_rcp_f32_e32 v43, v35
	v_readlane_b32 s24, v255, 11
	v_readlane_b32 s25, v255, 12
	v_fma_f32 v69, -v35, v43, 1.0
	v_fmac_f32_e32 v43, v69, v43
	v_div_scale_f32 v69, vcc, 1.0, v33, 1.0
	v_mul_f32_e32 v74, v69, v43
	v_fma_f32 v75, -v35, v74, v69
	v_fmac_f32_e32 v74, v75, v43
	v_fma_f32 v35, -v35, v74, v69
	v_div_fmas_f32 v35, v35, v43, v74
	v_div_fixup_f32 v76, v35, v33, 1.0
	v_mov_b32_e32 v74, v44
	v_mov_b32_e32 v75, v72
	v_pk_mul_f32 v[80:81], v[74:75], v[76:77] op_sel_hi:[1,0]
	v_mov_b32_e32 v44, v73
	v_pk_fma_f32 v[72:73], v[0:1], v[80:81], v[4:5]
	v_pk_mul_f32 v[44:45], v[44:45], v[76:77] op_sel_hi:[1,0]
	v_bfe_u32 v33, v72, 16, 1
	v_add3_u32 v33, v72, v33, s6
	v_bfe_u32 v35, v73, 16, 1
	v_pk_fma_f32 v[74:75], v[2:3], v[44:45], v[6:7]
	v_lshrrev_b32_e32 v33, 16, v33
	v_add3_u32 v35, v73, v35, s6
	v_and_or_b32 v44, v35, s3, v33
	v_bfe_u32 v33, v74, 16, 1
	v_add3_u32 v33, v74, v33, s6
	v_bfe_u32 v35, v75, 16, 1
	global_store_dwordx4 v[62:63], v[72:75], off
	v_lshrrev_b32_e32 v33, 16, v33
	v_add3_u32 v35, v75, v35, s6
	v_add_co_u32_e32 v74, vcc, s0, v78
	v_and_or_b32 v45, v35, s3, v33
	s_nop 0
	v_addc_co_u32_e32 v75, vcc, 0, v79, vcc
	global_store_dwordx2 v[74:75], v[44:45], off
	v_mov_b32_e32 v44, v40
	v_mov_b32_e32 v45, v70
	v_pk_mul_f32 v[44:45], v[44:45], v[76:77] op_sel_hi:[1,0]
	v_mov_b32_e32 v40, v71
	v_pk_fma_f32 v[70:71], v[8:9], v[44:45], v[12:13]
	v_pk_mul_f32 v[40:41], v[40:41], v[76:77] op_sel_hi:[1,0]
	v_bfe_u32 v33, v70, 16, 1
	v_add3_u32 v33, v70, v33, s6
	v_bfe_u32 v35, v71, 16, 1
	v_pk_fma_f32 v[72:73], v[10:11], v[40:41], v[14:15]
	v_lshrrev_b32_e32 v33, 16, v33
	v_add3_u32 v35, v71, v35, s6
	v_and_or_b32 v40, v35, s3, v33
	v_bfe_u32 v33, v72, 16, 1
	v_add3_u32 v33, v72, v33, s6
	v_bfe_u32 v35, v73, 16, 1
	v_pk_mul_f32 v[36:37], v[36:37], v[76:77] op_sel_hi:[1,0]
	v_lshrrev_b32_e32 v33, 16, v33
	v_add3_u32 v35, v73, v35, s6
	v_pk_fma_f32 v[36:37], v[16:17], v[36:37], v[20:21]
	v_and_or_b32 v41, v35, s3, v33
	v_bfe_u32 v33, v36, 16, 1
	v_pk_mul_f32 v[38:39], v[38:39], v[76:77] op_sel_hi:[1,0]
	v_add3_u32 v33, v36, v33, s6
	v_bfe_u32 v35, v37, 16, 1
	v_pk_fma_f32 v[38:39], v[18:19], v[38:39], v[22:23]
	v_lshrrev_b32_e32 v33, 16, v33
	v_add3_u32 v35, v37, v35, s6
	global_store_dwordx4 v[62:63], v[70:73], off offset:1024
	global_store_dwordx2 v[74:75], v[40:41], off offset:512
	global_store_dwordx4 v[62:63], v[36:39], off offset:2048
	v_lshl_add_u64 v[66:67], v[66:67], 0, s[24:25]
	s_andn2_b64 vcc, exec, s[12:13]
	v_and_or_b32 v36, v35, s3, v33
	v_bfe_u32 v33, v38, 16, 1
	v_add3_u32 v33, v38, v33, s6
	v_bfe_u32 v35, v39, 16, 1
	v_lshrrev_b32_e32 v33, 16, v33
	v_add3_u32 v35, v39, v35, s6
	v_and_or_b32 v37, v35, s3, v33
	v_mov_b32_e32 v33, v42
	v_pk_mul_f32 v[32:33], v[32:33], v[76:77] op_sel_hi:[1,0]
	v_mov_b32_e32 v35, v68
	v_pk_mul_f32 v[34:35], v[34:35], v[76:77] op_sel_hi:[1,0]
	v_pk_fma_f32 v[32:33], v[24:25], v[32:33], v[28:29]
	global_store_dwordx2 v[74:75], v[36:37], off offset:1024
	v_pk_fma_f32 v[34:35], v[26:27], v[34:35], v[30:31]
	v_bfe_u32 v36, v32, 16, 1
	global_store_dwordx4 v[62:63], v[32:35], off offset:3072
	v_lshl_add_u64 v[62:63], v[62:63], 0, s[24:25]
	s_nop 1
	v_add3_u32 v32, v32, v36, s6
	v_bfe_u32 v36, v33, 16, 1
	v_lshrrev_b32_e32 v32, 16, v32
	v_add3_u32 v33, v33, v36, s6
	v_and_or_b32 v32, v33, s3, v32
	v_bfe_u32 v33, v34, 16, 1
	v_add3_u32 v33, v34, v33, s6
	v_bfe_u32 v34, v35, 16, 1
	v_lshrrev_b32_e32 v33, 16, v33
	v_add3_u32 v34, v35, v34, s6
	v_and_or_b32 v33, v34, s3, v33
	global_store_dwordx2 v[74:75], v[32:33], off offset:1536
	v_readlane_b32 s12, v255, 13
	s_add_i32 s2, s2, s12
	s_cmpk_gt_i32 s2, 0x40ff
	s_cbranch_scc1 .LBB0_1645
	s_waitcnt vmcnt(12)
	v_mov_b32_e32 v44, v96
	v_mov_b32_e32 v72, v97
	v_mov_b32_e32 v73, v98
	v_mov_b32_e32 v45, v99
	v_mov_b32_e32 v40, v100
	v_mov_b32_e32 v70, v101
	v_mov_b32_e32 v71, v102
	v_mov_b32_e32 v41, v103
	v_mov_b32_e32 v36, v104
	v_mov_b32_e32 v37, v105
	v_mov_b32_e32 v38, v106
	v_mov_b32_e32 v39, v107
	v_mov_b32_e32 v32, v108
	v_mov_b32_e32 v42, v109
	v_mov_b32_e32 v34, v110
	v_mov_b32_e32 v68, v111
	s_lshl_b32 s13, s12, 1
	s_add_i32 s13, s13, s2
	s_cmpk_gt_i32 s13, 0x40ff
	s_cbranch_scc1 .Lln_B_noload
	v_lshl_add_u64 v[112:113], v[66:67], 0, s[24:25]
	v_lshl_add_u64 v[112:113], s[88:89], 0, v[112:113]
	v_add_co_u32_e32 v112, vcc, 0x14800000, v112
	s_nop 1
	v_addc_co_u32_e32 v113, vcc, 0, v113, vcc
	global_load_dwordx4 v[96:99], v[112:113], off
	global_load_dwordx4 v[100:103], v[112:113], off offset:1024
	global_load_dwordx4 v[104:107], v[112:113], off offset:2048
	global_load_dwordx4 v[108:111], v[112:113], off offset:3072
.Lln_B_noload:
	s_branch .Lln_A
.LBB0_1645:
	s_mov_b32 s96, 0x88888889
